# online-softmax lazy rescale threshold 8 -> 64 (log2 units) in fox/DSA attention; exact softmax, fewer O rescales
# speedup vs baseline: 1.0037x; 1.0020x over previous
.LBB0_842:
	v_cmp_lt_f32_e32 vcc, 0x42800000, v1
	v_mov_b32_e32 v104, 1.0
	v_mov_b32_e32 v106, 0
	s_and_saveexec_b64 s[4:5], vcc
	v_exp_f32_e64 v104, -v1
	v_mov_b32_e32 v106, v1
	s_or_b64 exec, exec, s[4:5]
	s_or_saveexec_b64 s[4:5], s[0:1]
	s_mov_b64 s[0:1], 0
	s_xor_b64 exec, exec, s[4:5]
	s_cbranch_execz .LBB0_829

.LBB0_848:
	v_cmp_lt_f32_e32 vcc, 0x42800000, v1
	v_mov_b32_e32 v106, 0
	v_mov_b32_e32 v104, 1.0
	s_and_saveexec_b64 s[4:5], vcc
	v_exp_f32_e64 v104, -v1
	v_mov_b32_e32 v106, v1
	s_or_b64 exec, exec, s[4:5]
	s_or_saveexec_b64 s[4:5], s[0:1]
	s_mov_b64 s[0:1], 0
	s_xor_b64 exec, exec, s[4:5]
	s_cbranch_execz .LBB0_837

.LBB0_934:
	v_cmp_lt_f32_e32 vcc, 0x42800000, v1
	v_mov_b32_e32 v108, 1.0
	v_mov_b32_e32 v110, 0
	s_and_saveexec_b64 s[12:13], vcc
	v_exp_f32_e64 v108, -v1
	v_mov_b32_e32 v110, v1
	s_or_b64 exec, exec, s[12:13]
	s_or_saveexec_b64 s[12:13], s[10:11]
	s_mov_b64 s[10:11], 0
	s_xor_b64 exec, exec, s[12:13]
	s_cbranch_execz .LBB0_923

.LBB0_940:
	v_cmp_lt_f32_e32 vcc, 0x42800000, v1
	v_mov_b32_e32 v110, 0
	v_mov_b32_e32 v108, 1.0
	s_and_saveexec_b64 s[12:13], vcc
	v_exp_f32_e64 v108, -v1
	v_mov_b32_e32 v110, v1
	s_or_b64 exec, exec, s[12:13]
	s_or_saveexec_b64 s[12:13], s[10:11]
	s_mov_b64 s[10:11], 0
	s_xor_b64 exec, exec, s[12:13]
	s_cbranch_execz .LBB0_929
